# MLA: rescale test against a per-lane threshold register (no per-sub-tile alpha math), SGPR-base tile loads with 32-bit offsets
# speedup vs baseline: 1.0247x; 1.0114x over previous
; DI void mla_load(const bf16_t* KNOPE, const bf16_t* KROPE, const bf16_t* VT, int h, size_t tokb, int kt, u32x4 (&r)[5], int tid) {
; #pragma unroll
;     for (int i = 0; i < 2; ++i) { const int q = tid + 512 * i, key = q >> 4, ch = q & 15;
;         r[i] = *(const u32x4*)(KNOPE + (tokb + kt * 64 + key) * 1024 + h * 128 + 8 * ch); }
;     { const int key = tid >> 3, ch = tid & 7; r[2] = *(const u32x4*)(KROPE + (tokb + kt * 64 + key) * 64 + 8 * ch); }
; #pragma unroll
;     for (int i = 0; i < 2; ++i) { const int q = tid + 512 * i, d = q >> 3, ch = q & 7;
;         r[3 + i] = *(const u32x4*)(VT + (size_t)(h * 128 + d) * T_ + tokb + kt * 64 + 8 * ch); }
; }
; DI void mla_unit(const Params& p, LAS unsigned char* lds, int b, int h, int qb, int tid) {
;     ...
;     const int lane = tid & 63, w = __builtin_amdgcn_readfirstlane(tid >> 6), c = lane & 31, hi = lane >> 5;
;     const int q0 = qb * 256, qw0 = q0 + 32 * w, qpos = qw0 + c;
;     const size_t tokb = (size_t)b * S_;
;     bf16x8 qf[12];
;     { const bf16_t* qp = QMLA + (tokb + qpos) * 1536 + h * 192 + 8 * hi;
; #pragma unroll
;       for (int st = 0; st < 12; ++st) qf[st] = *(const bf16x8*)(qp + 16 * st); }
;     f32x16 o[4];
; #pragma unroll
;     for (int db = 0; db < 4; ++db)
; #pragma unroll
;         for (int i = 0; i < 16; ++i) o[db][i] = 0.f;
;     float m = -1e20f, l = 0.f;
;     const int nkt = 4 * qb + 4;
;     u32x4 r[5];
;     __syncthreads();
;     mla_load(KNOPE, KROPE, VT, h, tokb, 0, r, tid); mla_store(lds, r, tid);
;     __syncthreads();
;     for (int kt = 0; kt < nkt; ++kt) {
;         const bool more = kt + 1 < nkt;
;         if (more) mla_load(KNOPE, KROPE, VT, h, tokb, kt + 1, r, tid);
.LBB0_618:
	s_or_b64 exec, exec, s[2:3]
	v_mov_b32_e32 v1, s1
	s_waitcnt lgkmcnt(0)
	s_barrier
	ds_read_b32 v1, v1
	s_movk_i32 s2, 0x7f
	s_waitcnt lgkmcnt(0)
	v_cmp_lt_i32_e32 vcc, s2, v1
	v_readfirstlane_b32 s4, v1
	s_mov_b64 s[2:3], -1
	s_cbranch_vccnz .LBB0_613
	s_not_b32 s2, s4
	s_bfe_u32 s8, s2, 0x50001
	s_ashr_i32 s2, s4, 5
	s_and_b32 s2, s2, -2
	s_and_b32 s3, s4, 1
	s_or_b32 s2, s2, s3
	v_readfirstlane_b32 s3, v0
	s_ashr_i32 s3, s3, 1
	s_lshl_b32 s79, s8, 8
	s_and_b32 s58, s3, 0xffffffe0
	v_and_b32_e32 v1, 31, v0
	s_add_i32 s58, s58, s79
	v_or_b32_e32 v2, s58, v1
	s_ashr_i32 s3, s2, 31
	s_lshl_b64 s[4:5], s[2:3], 13
	v_ashrrev_i32_e32 v3, 31, v2
	v_lshl_add_u64 v[150:151], s[4:5], 0, v[2:3]
	v_mov_b64_e32 v[4:5], s[70:71]
	v_add_u32_e32 v17, 0x200, v0
	v_bfe_u32 v16, v0, 5, 1
	v_mad_u64_u32 v[4:5], s[6:7], v150, s12, v[4:5]
	v_ashrrev_i32_e32 v6, 4, v0
	v_ashrrev_i32_e32 v10, 4, v17
	v_mad_i32_i24 v5, v151, s12, v5
	v_lshlrev_b32_e32 v148, 4, v16
	v_lshlrev_b32_e32 v3, 4, v0
	v_ashrrev_i32_e32 v7, 31, v6
	v_ashrrev_i32_e32 v11, 31, v10
	v_lshl_add_u64 v[4:5], v[4:5], 0, v[148:149]
	v_and_b32_e32 v152, 0xf0, v3
	v_mov_b32_e32 v153, v149
	v_lshl_add_u64 v[8:9], s[4:5], 0, v[6:7]
	v_lshl_add_u64 v[12:13], s[4:5], 0, v[10:11]
	global_load_dwordx4 v[80:83], v[4:5], off
	global_load_dwordx4 v[84:87], v[4:5], off offset:32
	global_load_dwordx4 v[88:91], v[4:5], off offset:64
	global_load_dwordx4 v[92:95], v[4:5], off offset:96
	global_load_dwordx4 v[96:99], v[4:5], off offset:128
	global_load_dwordx4 v[100:103], v[4:5], off offset:160
	global_load_dwordx4 v[104:107], v[4:5], off offset:192
	global_load_dwordx4 v[108:111], v[4:5], off offset:224
	global_load_dwordx4 v[112:115], v[4:5], off offset:256
	global_load_dwordx4 v[116:119], v[4:5], off offset:288
	global_load_dwordx4 v[120:123], v[4:5], off offset:320
	global_load_dwordx4 v[124:127], v[4:5], off offset:352
	v_lshl_add_u64 v[4:5], s[72:73], 0, v[152:153]
	v_lshlrev_b64 v[8:9], 11, v[8:9]
	v_lshlrev_b64 v[12:13], 11, v[12:13]
	v_lshl_add_u64 v[8:9], v[4:5], 0, v[8:9]
	v_lshl_add_u64 v[4:5], v[4:5], 0, v[12:13]
	s_barrier
	global_load_dwordx4 v[128:131], v[8:9], off
	global_load_dwordx4 v[132:135], v[4:5], off
	v_ashrrev_i32_e32 v4, 3, v0
	s_lshl_b32 s59, s8, 2
	v_ashrrev_i32_e32 v5, 31, v4
	s_add_i32 s59, s59, 4
	v_lshl_add_u64 v[8:9], s[4:5], 0, v[4:5]
	s_lshl_b64 s[4:5], s[2:3], 14
	v_lshlrev_b64 v[8:9], 7, v[8:9]
	s_add_u32 s6, s52, s4
	v_add_u32_e32 v14, s42, v4
	v_lshl_add_u64 v[8:9], s[54:55], 0, v[8:9]
	v_and_b32_e32 v154, 0x70, v3
	v_mov_b32_e32 v155, v149
	s_addc_u32 s7, s53, s5
	v_ashrrev_i32_e32 v15, 31, v14
	v_lshl_add_u64 v[8:9], v[8:9], 0, v[154:155]
	v_lshl_add_u64 v[12:13], s[6:7], 0, v[154:155]
	v_lshlrev_b64 v[14:15], 16, v[14:15]
	v_lshl_add_u64 v[14:15], v[12:13], 0, v[14:15]
	global_load_dwordx4 v[136:139], v[8:9], off
	global_load_dwordx4 v[140:143], v[14:15], off
	v_ashrrev_i32_e32 v8, 3, v17
	v_add_u32_e32 v14, s42, v8
	v_ashrrev_i32_e32 v15, 31, v14
	v_lshlrev_b64 v[14:15], 16, v[14:15]
	v_lshl_add_u64 v[12:13], v[12:13], 0, v[14:15]
	global_load_dwordx4 v[144:147], v[12:13], off
	v_mul_lo_u32 v171, v6, s13
	v_add_u32_e32 v3, 0, v152
	v_mul_lo_u32 v173, v10, s13
	v_add_u32_e32 v9, v3, v171
	v_add_u32_e32 v3, v3, v173
	v_mul_lo_u32 v172, v4, s13
	v_mul_lo_u32 v175, v4, s33
	v_mul_lo_u32 v176, v8, s33
	s_or_b32 s78, s58, 31
	v_lshlrev_b32_e32 v174, 2, v16
	s_add_u32 s4, s4, s43
	v_sub_u32_e32 v179, v2, v174
	s_addc_u32 s5, s5, s48
	v_and_b32_e32 v0, 15, v0
	v_mul_u32_u24_e32 v177, 0x88, v1
	v_mul_u32_u24_e32 v178, 0x190, v1
	v_lshlrev_b32_e32 v0, 4, v0
	v_mov_b32_e32 v1, v149
	v_mov_b32_e32 v14, v149
	v_mov_b32_e32 v15, v149
	v_lshlrev_b32_e32 v153, 3, v16
	v_mov_b32_e32 v12, v149
	v_mov_b32_e32 v13, v149
	s_mov_b32 s80, 0
	v_mov_b32_e32 v180, 0xe0ad78ec
	v_mov_b32_e32 v240, 0
	v_mov_b32_e32 v241, 0
	v_mov_b32_e32 v242, 0
	v_mov_b32_e32 v243, 0
	v_mov_b32_e32 v244, 0
	v_mov_b32_e32 v245, 0
	v_mov_b32_e32 v246, 0
	v_mov_b32_e32 v247, 0
	v_mov_b32_e32 v248, 0
	v_mov_b32_e32 v249, 0
	v_mov_b32_e32 v250, 0
	v_mov_b32_e32 v251, 0
	v_mov_b32_e32 v252, 0
	v_mov_b32_e32 v253, 0
	v_mov_b32_e32 v254, 0
	v_mov_b32_e32 v255, 0
	v_mov_b32_e32 v235, 0xe0ad78ec
	s_waitcnt vmcnt(4)
	ds_write_b128 v9, v[128:131]
	s_waitcnt vmcnt(3)
	ds_write_b128 v3, v[132:135]
	v_add_u32_e32 v3, 0, v154
	v_add_u32_e32 v9, v3, v172
	s_waitcnt vmcnt(2)
	ds_write_b128 v9, v[136:139] offset:256
	v_add3_u32 v9, v3, v175, s40
	v_add3_u32 v3, v3, v176, s40
	s_waitcnt vmcnt(1)
	ds_write2_b64 v9, v[140:141], v[142:143] offset1:1
	v_ashrrev_i32_e32 v9, 31, v8
	s_waitcnt vmcnt(0)
	ds_write2_b64 v3, v[144:145], v[146:147] offset1:1
	v_lshlrev_b64 v[2:3], 16, v[4:5]
	v_lshl_add_u64 v[2:3], s[4:5], 0, v[2:3]
	v_lshl_add_u64 v[156:157], v[2:3], 0, v[154:155]
	v_lshlrev_b64 v[2:3], 16, v[8:9]
	v_lshl_add_u64 v[2:3], s[4:5], 0, v[2:3]
	s_lshl_b64 s[4:5], s[2:3], 20
	s_add_u32 s4, s4, 0x2f002000
	s_addc_u32 s5, s5, 0
	s_lshl_b64 s[2:3], s[2:3], 24
	v_lshl_add_u64 v[158:159], v[2:3], 0, v[154:155]
	v_lshlrev_b64 v[2:3], 7, v[4:5]
	s_add_u32 s2, s49, s2
	v_lshl_add_u64 v[160:161], s[4:5], 0, v[2:3]
	s_addc_u32 s3, 0, s3
	v_lshlrev_b64 v[2:3], 11, v[10:11]
	v_lshl_add_u64 v[2:3], s[2:3], 0, v[2:3]
	v_lshl_add_u64 v[162:163], v[2:3], 0, v[0:1]
	v_lshlrev_b64 v[2:3], 11, v[6:7]
	v_lshl_add_u64 v[2:3], s[2:3], 0, v[2:3]
	v_lshl_add_u64 v[164:165], v[2:3], 0, v[0:1]
	v_mov_b32_e32 v0, v149
	v_mov_b32_e32 v2, v149
	v_mov_b32_e32 v3, v149
	v_mov_b32_e32 v4, v149
	v_mov_b32_e32 v5, v149
	v_mov_b32_e32 v6, v149
	v_mov_b32_e32 v7, v149
	v_mov_b32_e32 v8, v149
	v_mov_b32_e32 v9, v149
	v_mov_b32_e32 v10, v149
	v_mov_b32_e32 v11, v149
	v_mov_b64_e32 v[30:31], v[14:15]
	v_mov_b64_e32 v[46:47], v[14:15]
	v_mov_b64_e32 v[62:63], v[14:15]
	v_or_b32_e32 v160, v160, v154
	s_addk_i32 s79, 0x100
	v_mov_b32_e32 v155, 0
	v_mov_b64_e32 v[28:29], v[12:13]
	v_mov_b64_e32 v[26:27], v[10:11]
	v_mov_b64_e32 v[24:25], v[8:9]
	v_mov_b64_e32 v[22:23], v[6:7]
	v_mov_b64_e32 v[20:21], v[4:5]
	v_mov_b64_e32 v[18:19], v[2:3]
	v_mov_b64_e32 v[16:17], v[0:1]
	v_mov_b64_e32 v[44:45], v[12:13]
	v_mov_b64_e32 v[42:43], v[10:11]
	v_mov_b64_e32 v[40:41], v[8:9]
	v_mov_b64_e32 v[38:39], v[6:7]
	v_mov_b64_e32 v[36:37], v[4:5]
	v_mov_b64_e32 v[34:35], v[2:3]
	v_mov_b64_e32 v[32:33], v[0:1]
	v_mov_b64_e32 v[60:61], v[12:13]
	v_mov_b64_e32 v[58:59], v[10:11]
	v_mov_b64_e32 v[56:57], v[8:9]
	v_mov_b64_e32 v[54:55], v[6:7]
	v_mov_b64_e32 v[52:53], v[4:5]
	v_mov_b64_e32 v[50:51], v[2:3]
	v_mov_b64_e32 v[48:49], v[0:1]
	s_mov_b32 s2, 0
	s_waitcnt lgkmcnt(0)
	s_barrier
.LBB0_620:
	s_add_i32 s81, s2, 1
	s_cmp_lt_u32 s81, s59
	s_cselect_b64 s[76:77], -1, 0
	s_cmp_ge_u32 s81, s59
	s_cbranch_scc1 .LBB0_626
	global_load_dwordx4 v[128:131], v164, s[62:63]
	global_load_dwordx4 v[132:135], v162, s[62:63]
	global_load_dwordx4 v[136:139], v160, s[62:63]
	global_load_dwordx4 v[140:143], v156, s[62:63]
	global_load_dwordx4 v[144:147], v158, s[62:63]
	s_cmp_gt_i32 s80, s78
	s_cbranch_scc0 .LBB0_627

; DI void mla_load(const bf16_t* KNOPE, const bf16_t* KROPE, const bf16_t* VT, int h, size_t tokb, int kt, u32x4 (&r)[5], int tid) {
; #pragma unroll
;     for (int i = 0; i < 2; ++i) { const int q = tid + 512 * i, key = q >> 4, ch = q & 15;
;         r[i] = *(const u32x4*)(KNOPE + (tokb + kt * 64 + key) * 1024 + h * 128 + 8 * ch); }
;     { const int key = tid >> 3, ch = tid & 7; r[2] = *(const u32x4*)(KROPE + (tokb + kt * 64 + key) * 64 + 8 * ch); }
; #pragma unroll
;     for (int i = 0; i < 2; ++i) { const int q = tid + 512 * i, d = q >> 3, ch = q & 7;
;         r[3 + i] = *(const u32x4*)(VT + (size_t)(h * 128 + d) * T_ + tokb + kt * 64 + 8 * ch); }
; }
; DI void mla_unit(const Params& p, LAS unsigned char* lds, int b, int h, int qb, int tid) {
;     ...
;         if (more) mla_store(lds + ((kt + 1) & 1) * MLA_BUF, r, tid);
;         __syncthreads();
;     }
.LBB0_624:
	s_add_i32 s80, s80, 64
	s_mov_b64 s[2:3], 0x2000
	v_subrev_u32_e32 v179, 64, v179
	v_add_u32_e32 v156, 0x80, v156
	v_add_u32_e32 v158, 0x80, v158
	v_add_u32_e32 v160, 0x2000, v160
	v_add_u32_e32 v162, 0x20000, v162
	s_cmp_lg_u32 s79, s80
	v_add_u32_e32 v164, 0x20000, v164
	s_waitcnt lgkmcnt(0)
	s_barrier
	s_cbranch_scc0 .LBB0_612
	s_mov_b32 s2, s81
	s_branch .LBB0_620

; DI float xhalf_max(float v) { unsigned a = __builtin_bit_cast(unsigned, v), b = a; swap32(a, b); return fmaxf(__builtin_bit_cast(float, a), __builtin_bit_cast(float, b)); }
; DI float fexp2(float x) { return __builtin_amdgcn_exp2f(x); }
; DI void mla_unit(const Params& p, LAS unsigned char* lds, int b, int h, int qb, int tid) {
;     ...
;                 float mx = max16(s);
;                 mx = xhalf_max(mx);
;                 const float mn = (mx > m + 8.f) ? mx : m, alpha = fexp2(m - mn); m = mn; l *= alpha;
;                 if (__any(alpha != 1.f)) {
; #pragma unroll
;                     for (int db = 0; db < 4; ++db) o[db] = o[db] * alpha;
;                 }
.Lmla_nomask_0:
	v_max3_f32 v236, v64, v65, v66
	v_max3_f32 v237, v67, v68, v69
	v_max3_f32 v238, v70, v71, v72
	v_max3_f32 v239, v73, v74, v75
	v_max3_f32 v236, v236, v76, v77
	v_max3_f32 v237, v237, v78, v79
	v_max3_f32 v236, v236, v237, v238
	v_max3_f32 v236, v236, v239, v239
	v_mov_b32_e32 v237, v236
	s_nop 1
	v_permlane32_swap_b32_e32 v236, v237
	s_nop 0
	v_max_f32_e32 v236, v236, v237
	v_cmp_gt_f32_e32 vcc, v236, v235
	s_cbranch_vccz .Lmla_norescale_0
	v_sub_f32_e32 v236, v236, v240
	s_nop 0
	v_cndmask_b32_e32 v237, v180, v236, vcc
	v_sub_f32_e32 v166, v180, v237
	v_mov_b32_e32 v180, v237
	v_exp_f32_e32 v166, v166
	s_nop 0
	v_mul_f32_e32 v155, v155, v166
	v_pk_mul_f32 v[62:63], v[62:63], v[166:167] op_sel_hi:[1,0]
	v_pk_mul_f32 v[60:61], v[60:61], v[166:167] op_sel_hi:[1,0]
	v_pk_mul_f32 v[58:59], v[58:59], v[166:167] op_sel_hi:[1,0]
	v_pk_mul_f32 v[56:57], v[56:57], v[166:167] op_sel_hi:[1,0]
	v_pk_mul_f32 v[54:55], v[54:55], v[166:167] op_sel_hi:[1,0]
	v_pk_mul_f32 v[52:53], v[52:53], v[166:167] op_sel_hi:[1,0]
	v_pk_mul_f32 v[50:51], v[50:51], v[166:167] op_sel_hi:[1,0]
	v_pk_mul_f32 v[48:49], v[48:49], v[166:167] op_sel_hi:[1,0]
	v_pk_mul_f32 v[46:47], v[46:47], v[166:167] op_sel_hi:[1,0]
	v_pk_mul_f32 v[44:45], v[44:45], v[166:167] op_sel_hi:[1,0]
	v_pk_mul_f32 v[42:43], v[42:43], v[166:167] op_sel_hi:[1,0]
	v_pk_mul_f32 v[40:41], v[40:41], v[166:167] op_sel_hi:[1,0]
	v_pk_mul_f32 v[38:39], v[38:39], v[166:167] op_sel_hi:[1,0]
	v_pk_mul_f32 v[36:37], v[36:37], v[166:167] op_sel_hi:[1,0]
	v_pk_mul_f32 v[34:35], v[34:35], v[166:167] op_sel_hi:[1,0]
	v_pk_mul_f32 v[32:33], v[32:33], v[166:167] op_sel_hi:[1,0]
	v_pk_mul_f32 v[30:31], v[30:31], v[166:167] op_sel_hi:[1,0]
	v_pk_mul_f32 v[28:29], v[28:29], v[166:167] op_sel_hi:[1,0]
	v_pk_mul_f32 v[26:27], v[26:27], v[166:167] op_sel_hi:[1,0]
	v_pk_mul_f32 v[24:25], v[24:25], v[166:167] op_sel_hi:[1,0]
	v_pk_mul_f32 v[22:23], v[22:23], v[166:167] op_sel_hi:[1,0]
	v_pk_mul_f32 v[20:21], v[20:21], v[166:167] op_sel_hi:[1,0]
	v_pk_mul_f32 v[18:19], v[18:19], v[166:167] op_sel_hi:[1,0]
	v_pk_mul_f32 v[16:17], v[16:17], v[166:167] op_sel_hi:[1,0]
	v_pk_mul_f32 v[14:15], v[14:15], v[166:167] op_sel_hi:[1,0]
	v_pk_mul_f32 v[12:13], v[12:13], v[166:167] op_sel_hi:[1,0]
	v_pk_mul_f32 v[10:11], v[10:11], v[166:167] op_sel_hi:[1,0]
	v_pk_mul_f32 v[8:9], v[8:9], v[166:167] op_sel_hi:[1,0]
	v_pk_mul_f32 v[6:7], v[6:7], v[166:167] op_sel_hi:[1,0]
	v_pk_mul_f32 v[4:5], v[4:5], v[166:167] op_sel_hi:[1,0]
	v_pk_mul_f32 v[2:3], v[2:3], v[166:167] op_sel_hi:[1,0]
	v_pk_mul_f32 v[0:1], v[0:1], v[166:167] op_sel_hi:[1,0]
	v_cmp_lt_f32_e32 vcc, 0xdf0ac723, v180
	v_mov_b32_e32 v237, 0x41000000
	v_mov_b32_e32 v236, 0xe0ad78ec
	v_cndmask_b32_e32 v238, 0, v180, vcc
	v_cndmask_b32_e32 v235, v236, v237, vcc
	v_add_f32_e32 v239, v238, v240
	v_sub_f32_e32 v240, v240, v239
	v_sub_f32_e32 v241, v241, v239
	v_sub_f32_e32 v242, v242, v239
	v_sub_f32_e32 v243, v243, v239
	v_sub_f32_e32 v244, v244, v239
	v_sub_f32_e32 v245, v245, v239
	v_sub_f32_e32 v246, v246, v239
	v_sub_f32_e32 v247, v247, v239
	v_sub_f32_e32 v248, v248, v239
	v_sub_f32_e32 v249, v249, v239
	v_sub_f32_e32 v250, v250, v239
	v_sub_f32_e32 v251, v251, v239
	v_sub_f32_e32 v252, v252, v239
	v_sub_f32_e32 v253, v253, v239
	v_sub_f32_e32 v254, v254, v239
	v_sub_f32_e32 v255, v255, v239
	v_sub_f32_e32 v64, v64, v239
	v_sub_f32_e32 v65, v65, v239
	v_sub_f32_e32 v66, v66, v239
	v_sub_f32_e32 v67, v67, v239
	v_sub_f32_e32 v68, v68, v239
	v_sub_f32_e32 v69, v69, v239
	v_sub_f32_e32 v70, v70, v239
	v_sub_f32_e32 v71, v71, v239
	v_sub_f32_e32 v72, v72, v239
	v_sub_f32_e32 v73, v73, v239
	v_sub_f32_e32 v74, v74, v239
	v_sub_f32_e32 v75, v75, v239
	v_sub_f32_e32 v76, v76, v239
	v_sub_f32_e32 v77, v77, v239
	v_sub_f32_e32 v78, v78, v239
	v_sub_f32_e32 v79, v79, v239
; #define LAS __attribute__((address_space(3)))
; DI float fexp2(float x) { return __builtin_amdgcn_exp2f(x); }
; #define MFMA32(a, b, c) __builtin_amdgcn_mfma_f32_32x32x16_bf16((a), (b), (c), 0, 0, 0)
; DI void mla_unit(const Params& p, LAS unsigned char* lds, int b, int h, int qb, int tid) {
;     ...
; #pragma unroll
;                 for (int st = 0; st < 12; ++st) {
;                     const bf16x8 a = *(LAS const bf16x8*)(buf + (32 * sub + c) * 400 + st * 32 + hi * 16);
;                     s = MFMA32(a, qf[st], s);
;                 }
;                 if (kbase + 31 > qw0) {
;                     int dbase = qpos - kbase - 4 * hi;
;                     asm volatile("" : "+v"(dbase));
; #pragma unroll
;                     for (int i = 0; i < 16; ++i) if ((dbase - ((i & 3) + 8 * (i >> 2))) < 0) s[i] = -1e30f;
;     ...
;                 float ps = 0.f;
; #pragma unroll
;                 for (int i = 0; i < 16; ++i) { const float pv = fexp2(s[i] - m); s[i] = pv; ps += pv; }
;                 l += ps;
;                 const bf16x8 pb0 = packp(s, 0), pb1 = packp(s, 1);
; #pragma unroll
;                 for (int db = 0; db < 4; ++db) {
;                     LAS const unsigned char* ap = buf + 25600 + (32 * db + c) * 136 + (32 * sub + 4 * hi) * 2;
;                     const bf16x8 v0 = cat4(*(LAS const bf16x4*)(ap), *(LAS const bf16x4*)(ap + 16));
;                     const bf16x8 v1 = cat4(*(LAS const bf16x4*)(ap + 32), *(LAS const bf16x4*)(ap + 48));
;                     o[db] = MFMA32(v0, pb0, o[db]); o[db] = MFMA32(v1, pb1, o[db]);
.Lmla_norescale_0:
	v_exp_f32_e32 v64, v64
	v_exp_f32_e32 v65, v65
	v_exp_f32_e32 v66, v66
	v_exp_f32_e32 v67, v67
	v_exp_f32_e32 v68, v68
	v_exp_f32_e32 v69, v69
	v_exp_f32_e32 v70, v70
	v_exp_f32_e32 v71, v71
	v_exp_f32_e32 v72, v72
	v_exp_f32_e32 v73, v73
	v_exp_f32_e32 v74, v74
	v_exp_f32_e32 v75, v75
	v_exp_f32_e32 v76, v76
	v_exp_f32_e32 v77, v77
	v_exp_f32_e32 v78, v78
	v_exp_f32_e32 v79, v79
	v_add_f32_e32 v236, v64, v65
	v_add_f32_e32 v237, v66, v67
	v_cvt_pk_bf16_f32 v198, v64, v65
	v_cvt_pk_bf16_f32 v199, v66, v67
	v_cvt_pk_bf16_f32 v200, v68, v69
	v_cvt_pk_bf16_f32 v201, v70, v71
	v_cvt_pk_bf16_f32 v202, v72, v73
	v_cvt_pk_bf16_f32 v203, v74, v75
	v_cvt_pk_bf16_f32 v204, v76, v77
	v_cvt_pk_bf16_f32 v205, v78, v79
	v_add_f32_e32 v238, v68, v69
	v_add_f32_e32 v239, v70, v71
	s_waitcnt lgkmcnt(5)
	v_mfma_f32_32x32x16_bf16 v[48:63], v[206:209], v[198:201], v[48:63]
	ds_read2_b64 v[206:209], v233 offset0:228 offset1:230
	v_add_f32_e32 v236, v236, v72
	v_add_f32_e32 v237, v237, v73
	s_waitcnt lgkmcnt(5)
	v_mfma_f32_32x32x16_bf16 v[48:63], v[210:213], v[202:205], v[48:63]
	ds_read2_b64 v[210:213], v233 offset0:224 offset1:226
	v_add_f32_e32 v238, v238, v74
	v_add_f32_e32 v239, v239, v75
	s_waitcnt lgkmcnt(5)
	v_mfma_f32_32x32x16_bf16 v[32:47], v[214:217], v[202:205], v[32:47]
	ds_read_b128 v[182:185], v168 offset:12800
	v_add_f32_e32 v236, v236, v76
	v_add_f32_e32 v237, v237, v77
	s_waitcnt lgkmcnt(5)
	v_mfma_f32_32x32x16_bf16 v[32:47], v[218:221], v[198:201], v[32:47]
	ds_read_b128 v[186:189], v168 offset:12832
	v_add_f32_e32 v238, v238, v78
	v_add_f32_e32 v239, v239, v79
	s_waitcnt lgkmcnt(5)
	v_mfma_f32_32x32x16_bf16 v[16:31], v[222:225], v[198:201], v[16:31]
	ds_read_b128 v[190:193], v168 offset:12864
	v_add_f32_e32 v236, v236, v237
	s_waitcnt lgkmcnt(5)
	v_mfma_f32_32x32x16_bf16 v[16:31], v[226:229], v[202:205], v[16:31]
	ds_read_b128 v[194:197], v168 offset:12896
	v_add_f32_e32 v238, v238, v239
	s_waitcnt lgkmcnt(5)
	v_mfma_f32_32x32x16_bf16 v[0:15], v[206:209], v[202:205], v[0:15]
	v_add_f32_e32 v236, v236, v238
	s_waitcnt lgkmcnt(4)
	v_mfma_f32_32x32x16_bf16 v[0:15], v[210:213], v[198:201], v[0:15]
	v_add_f32_e32 v155, v155, v236
	ds_read_b128 v[198:201], v168 offset:12928
	ds_read_b128 v[202:205], v168 offset:12960
	s_waitcnt lgkmcnt(5)
	v_mfma_f32_32x32x16_bf16 v[64:79], v[182:185], v[80:83], v[240:255]
	ds_read_b128 v[182:185], v168 offset:12992
	s_waitcnt lgkmcnt(5)
	v_mfma_f32_32x32x16_bf16 v[64:79], v[186:189], v[84:87], v[64:79]
	ds_read_b128 v[186:189], v168 offset:13024
	s_waitcnt lgkmcnt(5)
	v_mfma_f32_32x32x16_bf16 v[64:79], v[190:193], v[88:91], v[64:79]
	ds_read_b128 v[190:193], v168 offset:13056
	s_waitcnt lgkmcnt(5)
	v_mfma_f32_32x32x16_bf16 v[64:79], v[194:197], v[92:95], v[64:79]
	ds_read_b128 v[194:197], v168 offset:13088
	s_waitcnt lgkmcnt(5)
	v_mfma_f32_32x32x16_bf16 v[64:79], v[198:201], v[96:99], v[64:79]
	ds_read_b128 v[198:201], v168 offset:13120
	s_waitcnt lgkmcnt(5)
	v_mfma_f32_32x32x16_bf16 v[64:79], v[202:205], v[100:103], v[64:79]
	ds_read_b128 v[202:205], v168 offset:13152
	s_waitcnt lgkmcnt(5)
	v_mfma_f32_32x32x16_bf16 v[64:79], v[182:185], v[104:107], v[64:79]
	ds_read2_b64 v[206:209], v230 offset0:136 offset1:138
	s_waitcnt lgkmcnt(5)
	v_mfma_f32_32x32x16_bf16 v[64:79], v[186:189], v[108:111], v[64:79]
	ds_read2_b64 v[210:213], v230 offset0:140 offset1:142
	s_waitcnt lgkmcnt(5)
	v_mfma_f32_32x32x16_bf16 v[64:79], v[190:193], v[112:115], v[64:79]
	ds_read2_b64 v[214:217], v231 offset0:172 offset1:174
	s_waitcnt lgkmcnt(5)
	v_mfma_f32_32x32x16_bf16 v[64:79], v[194:197], v[116:119], v[64:79]
	ds_read2_b64 v[218:221], v231 offset0:168 offset1:170
	s_waitcnt lgkmcnt(5)
	v_mfma_f32_32x32x16_bf16 v[64:79], v[198:201], v[120:123], v[64:79]
	ds_read2_b64 v[222:225], v232 offset0:200 offset1:202
	s_waitcnt lgkmcnt(5)
	v_mfma_f32_32x32x16_bf16 v[64:79], v[202:205], v[124:127], v[64:79]
	ds_read2_b64 v[226:229], v232 offset0:204 offset1:206
	s_add_i32 s2, s80, 63
	s_cmp_le_i32 s2, s58
	s_nop 7
	s_cbranch_scc1 .Lmla_nomask_1
	v_subrev_u32_e32 v236, 32, v179
	s_nop 0
	v_cmp_gt_i32_e64 s[30:31], 26, v236
	v_cmp_gt_i32_e64 s[34:35], 27, v236
	v_cmp_gt_i32_e64 s[28:29], 25, v236
	s_and_b64 s[30:31], s[34:35], s[30:31]
	v_cmp_gt_i32_e64 s[26:27], 24, v236
	s_and_b64 s[28:29], s[30:31], s[28:29]
	v_cmp_gt_i32_e64 s[24:25], 19, v236
	s_and_b64 s[26:27], s[28:29], s[26:27]
	v_cmp_gt_i32_e64 s[22:23], 18, v236
	s_and_b64 s[24:25], s[26:27], s[24:25]
	v_cmp_gt_i32_e64 s[20:21], 17, v236
	s_and_b64 s[22:23], s[24:25], s[22:23]
	v_cmp_gt_i32_e64 s[18:19], 16, v236
	s_and_b64 s[20:21], s[22:23], s[20:21]
	v_cmp_gt_i32_e64 s[16:17], 11, v236
	s_and_b64 s[18:19], s[20:21], s[18:19]
	v_cmp_gt_i32_e64 s[14:15], 10, v236
	s_and_b64 s[16:17], s[18:19], s[16:17]
	v_cmp_gt_i32_e64 s[10:11], 9, v236
	s_and_b64 s[14:15], s[16:17], s[14:15]
	v_cmp_gt_i32_e64 s[8:9], 8, v236
	s_and_b64 s[10:11], s[14:15], s[10:11]
	v_cmp_gt_i32_e64 s[6:7], 3, v236
	s_and_b64 s[8:9], s[10:11], s[8:9]
	v_cmp_gt_i32_e64 s[4:5], 2, v236
	s_and_b64 s[6:7], s[8:9], s[6:7]
	v_cmp_gt_i32_e64 s[2:3], 1, v236
	s_and_b64 s[4:5], s[6:7], s[4:5]
	v_cmp_gt_i32_e32 vcc, 0, v236
	s_and_b64 s[2:3], s[4:5], s[2:3]
	s_and_b64 vcc, s[2:3], vcc
	s_nop 1
	v_cndmask_b32_e64 v79, v79, v170, s[34:35]
	v_cndmask_b32_e64 v78, v78, v170, s[30:31]
	v_cndmask_b32_e64 v77, v77, v170, s[28:29]
	v_cndmask_b32_e64 v76, v76, v170, s[26:27]
	v_cndmask_b32_e64 v75, v75, v170, s[24:25]
	v_cndmask_b32_e64 v74, v74, v170, s[22:23]
	v_cndmask_b32_e64 v73, v73, v170, s[20:21]
	v_cndmask_b32_e64 v72, v72, v170, s[18:19]
	v_cndmask_b32_e64 v71, v71, v170, s[16:17]
	v_cndmask_b32_e64 v70, v70, v170, s[14:15]
	v_cndmask_b32_e64 v69, v69, v170, s[10:11]
	v_cndmask_b32_e64 v68, v68, v170, s[8:9]
	v_cndmask_b32_e64 v67, v67, v170, s[6:7]
	v_cndmask_b32_e64 v66, v66, v170, s[4:5]
	v_cndmask_b32_e64 v65, v65, v170, s[2:3]
	v_cndmask_b32_e32 v64, v64, v170, vcc

; #define LAS __attribute__((address_space(3)))
; DI float fexp2(float x) { return __builtin_amdgcn_exp2f(x); }
; #define MFMA32(a, b, c) __builtin_amdgcn_mfma_f32_32x32x16_bf16((a), (b), (c), 0, 0, 0)
; DI void mla_unit(const Params& p, LAS unsigned char* lds, int b, int h, int qb, int tid) {
;     ...
;                 float ps = 0.f;
; #pragma unroll
;                 for (int i = 0; i < 16; ++i) { const float pv = fexp2(s[i] - m); s[i] = pv; ps += pv; }
;                 l += ps;
;                 const bf16x8 pb0 = packp(s, 0), pb1 = packp(s, 1);
; #pragma unroll
;                 for (int db = 0; db < 4; ++db) {
;                     LAS const unsigned char* ap = buf + 25600 + (32 * db + c) * 136 + (32 * sub + 4 * hi) * 2;
;                     const bf16x8 v0 = cat4(*(LAS const bf16x4*)(ap), *(LAS const bf16x4*)(ap + 16));
;                     const bf16x8 v1 = cat4(*(LAS const bf16x4*)(ap + 32), *(LAS const bf16x4*)(ap + 48));
;                     o[db] = MFMA32(v0, pb0, o[db]); o[db] = MFMA32(v1, pb1, o[db]);
.Lmla_norescale_1:
	v_exp_f32_e32 v64, v64
	v_exp_f32_e32 v65, v65
	v_exp_f32_e32 v66, v66
	v_exp_f32_e32 v67, v67
	v_exp_f32_e32 v68, v68
	v_exp_f32_e32 v69, v69
	v_exp_f32_e32 v70, v70
	v_exp_f32_e32 v71, v71
	v_exp_f32_e32 v72, v72
	v_exp_f32_e32 v73, v73
	v_exp_f32_e32 v74, v74
	v_exp_f32_e32 v75, v75
	v_exp_f32_e32 v76, v76
	v_exp_f32_e32 v77, v77
	v_exp_f32_e32 v78, v78
	v_exp_f32_e32 v79, v79
	v_add_f32_e32 v236, v64, v65
	v_add_f32_e32 v237, v66, v67
	v_cvt_pk_bf16_f32 v198, v64, v65
	v_cvt_pk_bf16_f32 v199, v66, v67
	v_cvt_pk_bf16_f32 v200, v68, v69
	v_cvt_pk_bf16_f32 v201, v70, v71
	v_cvt_pk_bf16_f32 v202, v72, v73
	v_cvt_pk_bf16_f32 v203, v74, v75
	v_cvt_pk_bf16_f32 v204, v76, v77
	v_cvt_pk_bf16_f32 v205, v78, v79
	v_add_f32_e32 v238, v68, v69
	v_add_f32_e32 v239, v70, v71
	s_waitcnt lgkmcnt(5)
	v_mfma_f32_32x32x16_bf16 v[48:63], v[206:209], v[198:201], v[48:63]
	ds_read2_b64 v[206:209], v233 offset0:236 offset1:238
	v_add_f32_e32 v236, v236, v72
	v_add_f32_e32 v237, v237, v73
	s_waitcnt lgkmcnt(5)
	v_mfma_f32_32x32x16_bf16 v[48:63], v[210:213], v[202:205], v[48:63]
	ds_read2_b64 v[210:213], v233 offset0:232 offset1:234
	v_add_f32_e32 v238, v238, v74
	v_add_f32_e32 v239, v239, v75
	s_waitcnt lgkmcnt(5)
	v_mfma_f32_32x32x16_bf16 v[32:47], v[214:217], v[202:205], v[32:47]
	v_add_f32_e32 v236, v236, v76
	v_add_f32_e32 v237, v237, v77
	s_waitcnt lgkmcnt(4)
	v_mfma_f32_32x32x16_bf16 v[32:47], v[218:221], v[198:201], v[32:47]
	v_add_f32_e32 v238, v238, v78
	v_add_f32_e32 v239, v239, v79
	s_waitcnt lgkmcnt(3)
	v_mfma_f32_32x32x16_bf16 v[16:31], v[222:225], v[198:201], v[16:31]
	v_add_f32_e32 v236, v236, v237
	s_waitcnt lgkmcnt(2)
	v_mfma_f32_32x32x16_bf16 v[16:31], v[226:229], v[202:205], v[16:31]
	v_add_f32_e32 v238, v238, v239
	s_waitcnt lgkmcnt(1)
	v_mfma_f32_32x32x16_bf16 v[0:15], v[206:209], v[202:205], v[0:15]
	v_add_f32_e32 v236, v236, v238
	s_waitcnt lgkmcnt(0)
	v_mfma_f32_32x32x16_bf16 v[0:15], v[210:213], v[198:201], v[0:15]
	v_add_f32_e32 v155, v155, v236
	s_andn2_b64 vcc, exec, s[76:77]
	s_cbranch_vccz .LBB0_623
	s_branch .LBB0_624
